# v20 + per-unit accumulator zeroing with 64-bit moves
# speedup vs baseline: 1.0114x; 1.0024x over previous
; template <class Epi, class Sched, bool ALIGN_EPI = false, bool SP2 = false>
; __device__ __forceinline__ void gemm_phase(PG8_LAS unsigned char* lds, const Gemm g, const Sched& S, const Epi& E, int tid_in) {
;     ...
;         const char* nA = has_next ? (const char*)g.A + (size_t)nxt.pm * tstep : cA; const char* nB = has_next ? (const char*)g.Bt + (size_t)nxt.pn * tstep : cB;
;     ...
; #pragma unroll
;         for (int a = 0; a < 2; ++a)
; #pragma unroll
;             for (int b = 0; b < 2; ++b)
; #pragma unroll
;                 for (int m = 0; m < 4; ++m)
; #pragma unroll
;                     for (int n = 0; n < 2; ++n) acc[a][b][m][n] = (f32x4){0.f, 0.f, 0.f, 0.f};
.LBB0_157:
	s_ashr_i32 s79, s78, 31
	s_lshl_b64 s[22:23], s[78:79], 19
	s_add_u32 s80, s54, s22
	s_addc_u32 s81, s55, s23
	s_and_b64 s[22:23], s[38:39], exec
	s_cselect_b32 s21, s81, s85
	s_cselect_b32 s22, s80, s84
	s_ashr_i32 s77, s76, 31
	s_lshl_b64 s[24:25], s[76:77], 19
	v_readlane_b32 s8, v254, 8
	s_add_u32 s82, s8, s24
	v_readlane_b32 s8, v254, 10
	s_addc_u32 s83, s8, s25
	s_and_b64 s[24:25], s[38:39], exec
	s_cselect_b32 s23, s83, s87
	s_cselect_b32 s24, s82, s86
	s_add_u32 s84, s84, 0x40080
	s_addc_u32 s85, s85, 0
	s_add_u32 s25, s86, 0x100
	v_mov_b64_e32 v[0:1], 0
	s_addc_u32 s26, s87, 0
	s_mov_b32 s27, -2
	s_waitcnt lgkmcnt(0)
	v_mov_b64_e32 v[2:3], 0
	v_mov_b64_e32 v[4:5], 0
	v_mov_b64_e32 v[6:7], 0
	v_mov_b64_e32 v[16:17], 0
	v_mov_b64_e32 v[18:19], 0
	v_mov_b64_e32 v[20:21], 0
	v_mov_b64_e32 v[22:23], 0
	v_mov_b64_e32 v[40:41], 0
	v_mov_b64_e32 v[42:43], 0
	v_mov_b64_e32 v[52:53], 0
	v_mov_b64_e32 v[54:55], 0
	v_mov_b64_e32 v[64:65], 0
	v_mov_b64_e32 v[66:67], 0
	v_mov_b64_e32 v[68:69], 0
	v_mov_b64_e32 v[70:71], 0
	v_mov_b64_e32 v[8:9], 0
	v_mov_b64_e32 v[10:11], 0
	v_mov_b64_e32 v[12:13], 0
	v_mov_b64_e32 v[14:15], 0
	v_mov_b64_e32 v[24:25], 0
	v_mov_b64_e32 v[26:27], 0
	v_mov_b64_e32 v[28:29], 0
	v_mov_b64_e32 v[30:31], 0
	v_mov_b64_e32 v[56:57], 0
	v_mov_b64_e32 v[58:59], 0
	v_mov_b64_e32 v[60:61], 0
	v_mov_b64_e32 v[62:63], 0
	v_mov_b64_e32 v[72:73], 0
	v_mov_b64_e32 v[74:75], 0
	v_mov_b64_e32 v[76:77], 0
	v_mov_b64_e32 v[78:79], 0
	v_mov_b64_e32 v[82:83], 0
	v_mov_b64_e32 v[84:85], 0
	v_mov_b64_e32 v[86:87], 0
	v_mov_b64_e32 v[88:89], 0
	v_mov_b64_e32 v[98:99], 0
	v_mov_b64_e32 v[100:101], 0
	v_mov_b64_e32 v[102:103], 0
	v_mov_b64_e32 v[104:105], 0
	v_mov_b64_e32 v[114:115], 0
	v_mov_b64_e32 v[116:117], 0
	v_mov_b64_e32 v[118:119], 0
	v_mov_b64_e32 v[120:121], 0
	v_mov_b64_e32 v[130:131], 0
	v_mov_b64_e32 v[132:133], 0
	v_mov_b64_e32 v[134:135], 0
	v_mov_b64_e32 v[136:137], 0
	v_mov_b64_e32 v[90:91], 0
	v_mov_b64_e32 v[92:93], 0
	v_mov_b64_e32 v[94:95], 0
	v_mov_b64_e32 v[96:97], 0
	v_mov_b64_e32 v[106:107], 0
	v_mov_b64_e32 v[108:109], 0
	v_mov_b64_e32 v[110:111], 0
	v_mov_b64_e32 v[112:113], 0
	v_mov_b64_e32 v[122:123], 0
	v_mov_b64_e32 v[124:125], 0
	v_mov_b64_e32 v[126:127], 0
	v_mov_b64_e32 v[128:129], 0
	v_mov_b64_e32 v[138:139], 0
	v_mov_b64_e32 v[140:141], 0
	v_mov_b64_e32 v[142:143], 0
	v_mov_b64_e32 v[144:145], 0

; template <class Epi, class Sched, bool ALIGN_EPI = false, bool SP2 = false>
; __device__ __forceinline__ void gemm_phase(PG8_LAS unsigned char* lds, const Gemm g, const Sched& S, const Epi& E, int tid_in) {
;     ...
;         const char* nA = has_next ? (const char*)g.A + (size_t)nxt.pm * tstep : cA; const char* nB = has_next ? (const char*)g.Bt + (size_t)nxt.pn * tstep : cB;
;     ...
; #pragma unroll
;         for (int a = 0; a < 2; ++a)
; #pragma unroll
;             for (int b = 0; b < 2; ++b)
; #pragma unroll
;                 for (int m = 0; m < 4; ++m)
; #pragma unroll
;                     for (int n = 0; n < 2; ++n) acc[a][b][m][n] = (f32x4){0.f, 0.f, 0.f, 0.f};
.LBB0_439:
	s_ashr_i32 s9, s8, 31
	s_lshl_b64 s[72:73], s[8:9], 19
	s_add_u32 s10, s29, s72
	s_addc_u32 s11, s31, s73
	s_and_b64 s[74:75], s[36:37], exec
	s_cselect_b32 s71, s11, s79
	s_cselect_b32 s77, s10, s78
	s_ashr_i32 s67, s66, 31
	s_lshl_b64 s[74:75], s[66:67], 19
	v_readlane_b32 s9, v254, 4
	s_add_u32 s12, s9, s74
	v_readlane_b32 s9, v254, 6
	s_addc_u32 s13, s9, s75
	s_and_b64 s[82:83], s[36:37], exec
	s_cselect_b32 s67, s13, s81
	s_cselect_b32 s84, s12, s80
	s_add_u32 s78, s78, 0x40080
	s_addc_u32 s79, s79, 0
	s_add_u32 s85, s80, 0x100
	v_mov_b64_e32 v[0:1], 0
	s_addc_u32 s86, s81, 0
	s_mov_b32 s87, -2
	v_mov_b64_e32 v[2:3], 0
	v_mov_b64_e32 v[4:5], 0
	v_mov_b64_e32 v[6:7], 0
	v_mov_b64_e32 v[16:17], 0
	v_mov_b64_e32 v[18:19], 0
	v_mov_b64_e32 v[20:21], 0
	v_mov_b64_e32 v[22:23], 0
	v_mov_b64_e32 v[32:33], 0
	v_mov_b64_e32 v[34:35], 0
	v_mov_b64_e32 v[36:37], 0
	v_mov_b64_e32 v[38:39], 0
	v_mov_b64_e32 v[48:49], 0
	v_mov_b64_e32 v[50:51], 0
	v_mov_b64_e32 v[52:53], 0
	v_mov_b64_e32 v[54:55], 0
	v_mov_b64_e32 v[8:9], 0
	v_mov_b64_e32 v[10:11], 0
	v_mov_b64_e32 v[12:13], 0
	v_mov_b64_e32 v[14:15], 0
	v_mov_b64_e32 v[24:25], 0
	v_mov_b64_e32 v[26:27], 0
	v_mov_b64_e32 v[28:29], 0
	v_mov_b64_e32 v[30:31], 0
	v_mov_b64_e32 v[40:41], 0
	v_mov_b64_e32 v[42:43], 0
	v_mov_b64_e32 v[44:45], 0
	v_mov_b64_e32 v[46:47], 0
	v_mov_b64_e32 v[56:57], 0
	v_mov_b64_e32 v[58:59], 0
	v_mov_b64_e32 v[60:61], 0
	v_mov_b64_e32 v[62:63], 0
	v_mov_b64_e32 v[64:65], 0
	v_mov_b64_e32 v[66:67], 0
	v_mov_b64_e32 v[68:69], 0
	v_mov_b64_e32 v[70:71], 0
	v_mov_b64_e32 v[82:83], 0
	s_waitcnt vmcnt(0)
	v_mov_b64_e32 v[84:85], 0
	v_mov_b64_e32 v[86:87], 0
	v_mov_b64_e32 v[88:89], 0
	v_mov_b64_e32 v[94:95], 0
	v_mov_b64_e32 v[96:97], 0
	v_mov_b64_e32 v[102:103], 0
	v_mov_b64_e32 v[104:105], 0
	v_mov_b64_e32 v[110:111], 0
	v_mov_b64_e32 v[112:113], 0
	v_mov_b64_e32 v[118:119], 0
	v_mov_b64_e32 v[120:121], 0
	v_mov_b64_e32 v[72:73], 0
	v_mov_b64_e32 v[74:75], 0
	v_mov_b64_e32 v[76:77], 0
	v_mov_b64_e32 v[78:79], 0
	v_mov_b64_e32 v[90:91], 0
	v_mov_b64_e32 v[92:93], 0
	v_mov_b64_e32 v[98:99], 0
	v_mov_b64_e32 v[100:101], 0
	v_mov_b64_e32 v[106:107], 0
	v_mov_b64_e32 v[108:109], 0
	v_mov_b64_e32 v[114:115], 0
	v_mov_b64_e32 v[116:117], 0
	v_mov_b64_e32 v[122:123], 0
	v_mov_b64_e32 v[124:125], 0
	v_mov_b64_e32 v[126:127], 0
	v_mov_b64_e32 v[128:129], 0

; template <class Epi, class Sched, bool ALIGN_EPI = false, bool SP2 = false>
; __device__ __forceinline__ void gemm_phase(PG8_LAS unsigned char* lds, const Gemm g, const Sched& S, const Epi& E, int tid_in) {
;     ...
;         const char* nA = has_next ? (const char*)g.A + (size_t)nxt.pm * tstep : cA; const char* nB = has_next ? (const char*)g.Bt + (size_t)nxt.pn * tstep : cB;
;     ...
; #pragma unroll
;         for (int a = 0; a < 2; ++a)
; #pragma unroll
;             for (int b = 0; b < 2; ++b)
; #pragma unroll
;                 for (int m = 0; m < 4; ++m)
; #pragma unroll
;                     for (int n = 0; n < 2; ++n) acc[a][b][m][n] = (f32x4){0.f, 0.f, 0.f, 0.f};
.LBB0_507:
	s_add_u32 s40, s92, 0x80
	s_addc_u32 s41, s93, 0
	s_add_u32 s26, s42, 0x100
	v_mov_b64_e32 v[0:1], 0
	s_addc_u32 s27, s43, 0
	s_mov_b32 s42, 0
	s_waitcnt lgkmcnt(0)
	v_mov_b64_e32 v[2:3], 0
	v_mov_b64_e32 v[4:5], 0
	v_mov_b64_e32 v[6:7], 0
	v_mov_b64_e32 v[16:17], 0
	v_mov_b64_e32 v[18:19], 0
	v_mov_b64_e32 v[20:21], 0
	v_mov_b64_e32 v[22:23], 0
	v_mov_b64_e32 v[32:33], 0
	v_mov_b64_e32 v[34:35], 0
	v_mov_b64_e32 v[36:37], 0
	v_mov_b64_e32 v[38:39], 0
	v_mov_b64_e32 v[64:65], 0
	v_mov_b64_e32 v[66:67], 0
	v_mov_b64_e32 v[68:69], 0
	v_mov_b64_e32 v[70:71], 0
	v_mov_b64_e32 v[8:9], 0
	v_mov_b64_e32 v[10:11], 0
	v_mov_b64_e32 v[12:13], 0
	v_mov_b64_e32 v[14:15], 0
	v_mov_b64_e32 v[24:25], 0
	v_mov_b64_e32 v[26:27], 0
	v_mov_b64_e32 v[28:29], 0
	v_mov_b64_e32 v[30:31], 0
	v_mov_b64_e32 v[48:49], 0
	v_mov_b64_e32 v[50:51], 0
	v_mov_b64_e32 v[56:57], 0
	v_mov_b64_e32 v[58:59], 0
	v_mov_b64_e32 v[72:73], 0
	v_mov_b64_e32 v[74:75], 0
	v_mov_b64_e32 v[76:77], 0
	v_mov_b64_e32 v[78:79], 0
	v_mov_b64_e32 v[82:83], 0
	s_waitcnt vmcnt(0)
	v_mov_b64_e32 v[84:85], 0
	v_mov_b64_e32 v[86:87], 0
	v_mov_b64_e32 v[88:89], 0
	v_mov_b64_e32 v[98:99], 0
	v_mov_b64_e32 v[100:101], 0
	v_mov_b64_e32 v[102:103], 0
	v_mov_b64_e32 v[104:105], 0
	v_mov_b64_e32 v[114:115], 0
	v_mov_b64_e32 v[116:117], 0
	v_mov_b64_e32 v[118:119], 0
	v_mov_b64_e32 v[120:121], 0
	v_mov_b64_e32 v[130:131], 0
	v_mov_b64_e32 v[132:133], 0
	v_mov_b64_e32 v[134:135], 0
	v_mov_b64_e32 v[136:137], 0
	v_mov_b64_e32 v[90:91], 0
	v_mov_b64_e32 v[92:93], 0
	v_mov_b64_e32 v[94:95], 0
	v_mov_b64_e32 v[96:97], 0
	v_mov_b64_e32 v[106:107], 0
	v_mov_b64_e32 v[108:109], 0
	v_mov_b64_e32 v[110:111], 0
	v_mov_b64_e32 v[112:113], 0
	v_mov_b64_e32 v[122:123], 0
	v_mov_b64_e32 v[124:125], 0
	v_mov_b64_e32 v[126:127], 0
	v_mov_b64_e32 v[128:129], 0
	v_mov_b64_e32 v[138:139], 0
	v_mov_b64_e32 v[140:141], 0
	v_mov_b64_e32 v[142:143], 0
	v_mov_b64_e32 v[144:145], 0

; template <class Epi, class Sched, bool ALIGN_EPI = false, bool SP2 = false>
; __device__ __forceinline__ void gemm_phase(PG8_LAS unsigned char* lds, const Gemm g, const Sched& S, const Epi& E, int tid_in) {
;     ...
;         const char* nA = has_next ? (const char*)g.A + (size_t)nxt.pm * tstep : cA; const char* nB = has_next ? (const char*)g.Bt + (size_t)nxt.pn * tstep : cB;
;     ...
; #pragma unroll
;         for (int a = 0; a < 2; ++a)
; #pragma unroll
;             for (int b = 0; b < 2; ++b)
; #pragma unroll
;                 for (int m = 0; m < 4; ++m)
; #pragma unroll
;                     for (int n = 0; n < 2; ++n) acc[a][b][m][n] = (f32x4){0.f, 0.f, 0.f, 0.f};
.LBB0_779:
	s_ashr_i32 s45, s44, 31
	s_lshl_b64 s[52:53], s[44:45], 19
	s_add_u32 s52, s54, s52
	s_addc_u32 s53, s55, s53
	s_and_b64 s[64:65], s[36:37], exec
	s_cselect_b32 s45, s53, s69
	s_cselect_b32 s78, s52, s68
	s_ashr_i32 s43, s42, 31
	s_lshl_b64 s[64:65], s[42:43], 19
	s_add_u32 s64, s20, s64
	s_addc_u32 s65, s21, s65
	s_and_b64 s[72:73], s[36:37], exec
	s_cselect_b32 s43, s65, s71
	s_cselect_b32 s79, s64, s70
	s_add_u32 s68, s68, 0x40080
	s_addc_u32 s69, s69, 0
	s_add_u32 s80, s70, 0x100
	v_mov_b64_e32 v[0:1], 0
	s_addc_u32 s81, s71, 0
	s_mov_b32 s82, -2
	v_mov_b64_e32 v[2:3], 0
	v_mov_b64_e32 v[8:9], 0
	v_mov_b64_e32 v[10:11], 0
	v_mov_b64_e32 v[16:17], 0
	v_mov_b64_e32 v[18:19], 0
	v_mov_b64_e32 v[24:25], 0
	v_mov_b64_e32 v[26:27], 0
	v_mov_b64_e32 v[32:33], 0
	v_mov_b64_e32 v[34:35], 0
	v_mov_b64_e32 v[40:41], 0
	v_mov_b64_e32 v[42:43], 0
	v_mov_b64_e32 v[48:49], 0
	v_mov_b64_e32 v[50:51], 0
	v_mov_b64_e32 v[56:57], 0
	v_mov_b64_e32 v[58:59], 0
	v_mov_b64_e32 v[4:5], 0
	v_mov_b64_e32 v[6:7], 0
	v_mov_b64_e32 v[12:13], 0
	v_mov_b64_e32 v[14:15], 0
	v_mov_b64_e32 v[20:21], 0
	v_mov_b64_e32 v[22:23], 0
	v_mov_b64_e32 v[28:29], 0
	v_mov_b64_e32 v[30:31], 0
	v_mov_b64_e32 v[36:37], 0
	v_mov_b64_e32 v[38:39], 0
	v_mov_b64_e32 v[44:45], 0
	v_mov_b64_e32 v[46:47], 0
	v_mov_b64_e32 v[52:53], 0
	v_mov_b64_e32 v[54:55], 0
	v_mov_b64_e32 v[60:61], 0
	v_mov_b64_e32 v[62:63], 0
	v_mov_b64_e32 v[64:65], 0
	v_mov_b64_e32 v[66:67], 0
	v_mov_b64_e32 v[72:73], 0
	v_mov_b64_e32 v[74:75], 0
	v_mov_b64_e32 v[82:83], 0
	v_mov_b64_e32 v[84:85], 0
	v_mov_b64_e32 v[90:91], 0
	v_mov_b64_e32 v[92:93], 0
	v_mov_b64_e32 v[98:99], 0
	v_mov_b64_e32 v[100:101], 0
	v_mov_b64_e32 v[106:107], 0
	v_mov_b64_e32 v[108:109], 0
	v_mov_b64_e32 v[114:115], 0
	v_mov_b64_e32 v[116:117], 0
	v_mov_b64_e32 v[122:123], 0
	v_mov_b64_e32 v[124:125], 0
	v_mov_b64_e32 v[68:69], 0
	v_mov_b64_e32 v[70:71], 0
	v_mov_b64_e32 v[76:77], 0
	v_mov_b64_e32 v[78:79], 0
	v_mov_b64_e32 v[86:87], 0
	v_mov_b64_e32 v[88:89], 0
	v_mov_b64_e32 v[94:95], 0
	v_mov_b64_e32 v[96:97], 0
	v_mov_b64_e32 v[102:103], 0
	v_mov_b64_e32 v[104:105], 0
	v_mov_b64_e32 v[110:111], 0
	v_mov_b64_e32 v[112:113], 0
	v_mov_b64_e32 v[118:119], 0
	v_mov_b64_e32 v[120:121], 0
	v_mov_b64_e32 v[126:127], 0
	v_mov_b64_e32 v[128:129], 0
